# P2a->P2b grid barrier replaced by one-way counter signal: all blocks release+bump, only RWKV blocks wait+acquire
# baseline (speedup 1.0000x reference)
.LBB0_290:
	s_mov_b64 s[4:5], s[76:77]
	s_mov_b32 s1, s97
	s_mov_b32 s2, -1
	s_getreg_b32 s0, hwreg(HW_REG_XCC_ID, 0, 4)
	s_waitcnt vmcnt(0)
	s_nop 0
	v_mbcnt_lo_u32_b32 v0, s2, 0
	v_mbcnt_hi_u32_b32 v0, s2, v0
	v_lshl_or_b32 v0, s1, 6, v0
	v_cmp_eq_u32_e32 vcc, 0, v0
	s_barrier
	s_and_saveexec_b64 s[2:3], vcc
	s_cbranch_execz .LBB0_342
	s_load_dwordx2 s[6:7], s[4:5], 0xe0
	buffer_wbl2 sc1
	v_mov_b32_e32 v1, 0
	v_mov_b32_e32 v0, 1
	s_lshl_b32 s0, s90, 12
	s_waitcnt vmcnt(0) lgkmcnt(0)
	s_add_u32 s8, s6, s0
	s_addc_u32 s9, s7, 0
	s_add_u32 s8, s8, 0xcfc0
	s_addc_u32 s9, s9, 0
	global_atomic_add v1, v0, s[8:9]
	s_cmpk_lt_u32 s96, 0xb0
	s_cbranch_scc1 .Lsig_skip
	s_cmpk_gt_u32 s96, 0xef
	s_cbranch_scc1 .Lsig_skip
	s_mov_b32 s0, 0
.Lsig_spin:
	global_load_dword v2, v1, s[8:9] sc1
	s_add_i32 s0, s0, 1
	s_waitcnt vmcnt(0)
	v_cmp_gt_u32_e32 vcc, 0x100, v2
	s_cbranch_vccz .Lsig_got
	s_sleep 1
	s_cmp_lt_u32 s0, 0x20000
	s_cbranch_scc1 .Lsig_spin
.Lsig_got:
	buffer_inv sc1
.Lsig_skip:
	s_waitcnt vmcnt(0)
.LBB0_342:
	v_writelane_b32 v253, s49, 14
	v_writelane_b32 v253, s52, 15
	s_nop 1
	v_writelane_b32 v253, s53, 16
	s_or_b64 exec, exec, s[2:3]
	s_lshl_b32 s0, s90, 10
	s_mov_b32 s1, s93
	v_writelane_b32 v253, s0, 17
	s_mov_b64 s[2:3], s[76:77]
	s_waitcnt lgkmcnt(0)
	s_barrier
	v_writelane_b32 v253, s1, 18
	s_mul_i32 s0, s90, 0x380
	s_mov_b32 s1, s93
	s_load_dwordx16 s[4:19], s[2:3], 0x10
	v_writelane_b32 v253, s0, 19
	s_mov_b32 s85, s93
	s_nop 0
	v_writelane_b32 v253, s1, 20
	s_lshl_b32 s0, s90, 6
	s_mov_b32 s1, s93
	v_writelane_b32 v253, s0, 21
	s_nop 1
	v_writelane_b32 v253, s1, 22
	s_waitcnt lgkmcnt(0)
	v_writelane_b32 v253, s4, 23
	s_mov_b32 s1, s96
	s_mov_b32 s0, -1
	v_writelane_b32 v253, s5, 24
	v_writelane_b32 v253, s6, 25
	v_writelane_b32 v253, s7, 26
	v_writelane_b32 v253, s8, 27
	v_writelane_b32 v253, s9, 28
	v_writelane_b32 v253, s10, 29
	v_writelane_b32 v253, s11, 30
	v_writelane_b32 v253, s12, 31
	v_writelane_b32 v253, s13, 32
	v_writelane_b32 v253, s14, 33
	v_writelane_b32 v253, s15, 34
	v_writelane_b32 v253, s16, 35
	v_writelane_b32 v253, s17, 36
	v_writelane_b32 v253, s18, 37
	v_writelane_b32 v253, s19, 38
	s_load_dwordx8 s[76:83], s[2:3], 0xa0
	s_load_dwordx4 s[4:7], s[2:3], 0xc0
	s_load_dwordx2 s[72:73], s[2:3], 0xe0
	s_waitcnt lgkmcnt(0)
	v_writelane_b32 v253, s4, 39
	s_nop 1
	v_writelane_b32 v253, s5, 40
	v_writelane_b32 v253, s6, 41
	v_writelane_b32 v253, s7, 42
	s_mov_b64 s[4:5], -1
	v_readlane_b32 s6, v253, 14
	s_nop 0
	v_writelane_b32 v253, s0, 43
	s_mov_b32 s0, s97
	s_lshl_b32 s43, s0, 6
	s_add_u32 s44, s72, 0x3600000
	v_writelane_b32 v253, s0, 44
	s_addc_u32 s45, s73, 0
	s_cmp_gt_i32 s1, 63
	v_writelane_b32 v253, s44, 45
	s_nop 1
	v_writelane_b32 v253, s45, 46
	s_cbranch_scc0 .LBB0_756
	s_lshl_b32 s0, s90, 2
	v_writelane_b32 v253, s0, 47
	s_add_u32 s0, s72, 0x1600000
	v_writelane_b32 v253, s0, 48
	s_addc_u32 s0, s73, 0
	s_mul_i32 s4, s90, 0xc00
	v_writelane_b32 v253, s0, 50
	s_mov_b32 s5, s93
	s_cmpk_gt_u32 s1, 0x7f
	v_writelane_b32 v253, s4, 52
	s_nop 1
	v_writelane_b32 v253, s5, 53
	s_cbranch_scc0 .LBB0_361
	s_load_dwordx8 s[8:15], s[2:3], 0x50
	s_add_u32 s46, s72, 0xbe00000
	s_addc_u32 s47, s73, 0
	s_cmpk_gt_u32 s1, 0xaf
	s_waitcnt lgkmcnt(0)
	v_writelane_b32 v252, s8, 7
	s_nop 1
	v_writelane_b32 v252, s9, 8
	v_writelane_b32 v252, s10, 9
	v_writelane_b32 v252, s11, 10
	v_writelane_b32 v252, s12, 11
	v_writelane_b32 v252, s13, 12
	v_writelane_b32 v252, s14, 13
	v_writelane_b32 v252, s15, 14
	s_load_dwordx4 s[8:11], s[2:3], 0x70
	s_waitcnt lgkmcnt(0)
	v_writelane_b32 v252, s8, 15
	s_nop 1
	v_writelane_b32 v252, s9, 16
	v_writelane_b32 v252, s10, 17
	v_writelane_b32 v252, s11, 18
	s_cbranch_scc0 .LBB0_362
	s_cmpk_gt_u32 s1, 0xef
	s_cbranch_scc0 .LBB0_364
	s_mov_b32 s2, -1
	s_barrier
	s_add_i32 s0, s1, 0xffffff10
	v_mbcnt_lo_u32_b32 v0, s2, 0
	v_mbcnt_hi_u32_b32 v10, s2, v0
	v_or_b32_e32 v1, s43, v10
	s_cmp_gt_u32 s0, 63
	v_readfirstlane_b32 s18, v1
	s_cbranch_scc1 .LBB0_358
	v_lshlrev_b32_e32 v2, 4, v1
	v_add_u32_e32 v0, 0x2000, v2
	v_ashrrev_i32_e32 v4, 31, v0
	v_lshrrev_b32_e32 v4, 22, v4
	v_add_u32_e32 v4, v0, v4
	v_ashrrev_i32_e32 v4, 10, v4
	v_mul_i32_i24_e32 v5, 0x400, v4
	v_sub_u32_e32 v0, v0, v5
	v_lshrrev_b32_e32 v5, 4, v0
	v_bitop3_b32 v0, v5, v0, 32 bitop3:0x6c
	v_ashrrev_i32_e32 v5, 31, v0
	v_lshrrev_b32_e32 v5, 26, v5
	v_add_u32_e32 v6, v0, v5
	v_lshlrev_b32_e32 v7, 3, v4
	v_ashrrev_i32_e32 v5, 6, v6
	v_and_b32_e32 v7, -16, v7
	v_add_u32_e32 v7, v5, v7
	v_and_b32_e32 v8, 3, v5
	s_mov_b32 s4, 0x1fffe0
	v_lshrrev_b32_e32 v9, 2, v7
	v_lshlrev_b32_e32 v11, 1, v7
	v_and_b32_e32 v6, 0xc0, v6
	v_and_or_b32 v8, v7, s4, v8
	v_and_b32_e32 v9, 4, v9
	v_and_b32_e32 v11, 24, v11
	v_sub_u32_e32 v0, v0, v6
	v_or3_b32 v8, v8, v9, v11
	v_lshlrev_b32_e32 v9, 5, v4
	v_ashrrev_i16_sdwa v0, v230, sext(v0) dst_sel:DWORD dst_unused:UNUSED_PAD src0_sel:DWORD src1_sel:BYTE_0
	v_and_b32_e32 v9, 32, v9
	v_bfe_i32 v6, v0, 0, 16
	v_add_lshl_u32 v9, v9, v6, 1
	v_lshl_add_u32 v132, v7, 11, v9
	v_bfe_i32 v7, v1, 27, 1
	v_lshrrev_b32_e32 v7, 22, v7
	v_add_u32_e32 v7, v2, v7
	v_and_b32_e32 v7, 0xfffffc00, v7
	v_sub_u32_e32 v2, v2, v7
	v_lshl_add_u32 v0, v8, 11, v9
	v_lshrrev_b32_e32 v7, 4, v2
	v_ashrrev_i32_e32 v8, 31, v1
	v_bitop3_b32 v2, v7, v2, 32 bitop3:0x6c
	v_lshrrev_b32_e32 v8, 26, v8
	v_ashrrev_i32_e32 v7, 31, v2
	v_add_u32_e32 v1, v1, v8
	s_lshl_b64 s[2:3], s[92:93], 1
	v_lshrrev_b32_e32 v7, 26, v7
	v_ashrrev_i32_e32 v8, 6, v1
	s_add_u32 s2, s72, s2
	v_add_u32_e32 v9, v2, v7
	v_lshlrev_b32_e32 v1, 3, v8
	s_addc_u32 s3, s73, s3
	v_ashrrev_i32_e32 v7, 6, v9
	v_and_b32_e32 v1, -16, v1
	s_add_u32 s19, s2, 0x100000
	v_add_u32_e32 v1, v7, v1
	v_and_b32_e32 v11, 3, v7
	s_addc_u32 s20, s3, 0
	v_and_or_b32 v11, v1, s4, v11
	s_lshl_b32 s4, s0, 3
	s_lshr_b32 s5, s0, 4
	s_and_b32 s4, s4, 56
	s_or_b32 s30, s5, 12
	s_bfe_u32 s5, s1, 0x10003
	v_lshrrev_b32_e32 v12, 2, v1
	v_lshlrev_b32_e32 v13, 1, v1
	v_and_b32_e32 v9, 0xc0, v9
	s_or_b32 s4, s5, s4
	s_ashr_i32 s2, s18, 6
	v_and_b32_e32 v12, 4, v12
	v_and_b32_e32 v13, 24, v13
	v_sub_u32_e32 v2, v2, v9
	s_or_b32 s31, s4, 6
	s_ashr_i32 s3, s18, 8
	s_lshl_b32 s21, s2, 10
	v_or3_b32 v11, v11, v12, v13
	v_lshlrev_b32_e32 v12, 5, v8
	v_ashrrev_i16_sdwa v2, v230, sext(v2) dst_sel:DWORD dst_unused:UNUSED_PAD src0_sel:DWORD src1_sel:BYTE_0
	s_lshl_b32 s4, s31, 19
	s_lshl_b32 s5, s30, 19
	v_and_b32_e32 v12, 32, v12
	v_bfe_i32 v9, v2, 0, 16
	s_add_u32 s14, s19, s5
	v_add_lshl_u32 v12, v12, v9, 1
	s_addc_u32 s15, s20, 0
	s_add_i32 s22, s21, 0
	v_lshl_add_u32 v2, v11, 11, v12
	s_add_i32 m0, s22, 0x10000
	v_readlane_b32 s5, v253, 48
	global_load_lds_dwordx4 v2, s[14:15]
	s_add_i32 m0, s22, 0x12000
	s_add_u32 s12, s5, s4
	v_readlane_b32 s4, v253, 50
	v_lshl_add_u32 v134, v1, 11, v12
	global_load_lds_dwordx4 v0, s[14:15]
	s_addc_u32 s13, s4, 0
	s_mov_b32 m0, s22
	s_add_i32 s23, s22, 0x2000
	global_load_lds_dwordx4 v134, s[12:13]
	s_mov_b32 m0, s23
	s_add_u32 s4, s14, 0x40000
	global_load_lds_dwordx4 v132, s[12:13]
	s_addc_u32 s5, s15, 0
	s_add_i32 m0, s22, 0x14000
	s_nop 0
	global_load_lds_dwordx4 v2, s[4:5]
	s_add_i32 m0, s22, 0x16000
	s_nop 0
	global_load_lds_dwordx4 v0, s[4:5]
	s_add_u32 s4, s12, 0x40000
	s_addc_u32 s5, s13, 0
	s_add_i32 s24, s22, 0x4000
	s_mov_b32 m0, s24
	s_add_i32 s25, s22, 0x6000
	global_load_lds_dwordx4 v134, s[4:5]
	s_mov_b32 m0, s25
	s_cmp_lg_u32 s3, 1
	global_load_lds_dwordx4 v132, s[4:5]
	s_cbranch_scc1 .LBB0_349
	s_barrier
